# LRU strip start: conv-constant LDS fill rewritten (both loads in flight, writes and barrier deferred into the pass prologue)
# speedup vs baseline: 1.0129x; 1.0010x over previous
; #define LAS __attribute__((address_space(3)))
; __device__ __forceinline__ int opaque_tid() { int t = threadIdx.x; asm volatile("" : "+v"(t)); return t; }
; #define LDS_BARRIER() do { asm volatile("s_waitcnt lgkmcnt(0)" ::: "memory"); __builtin_amdgcn_s_barrier(); asm volatile("" ::: "memory"); } while (0)
; template <int dir>
; __device__ __forceinline__ void lru_pass(LAS unsigned char* lds, const Params& P, int b, int h, int q, bool dry) {
;     ...
;     {
; #pragma unroll
;         for (int i = 0; i < 2; ++i) { const int idx = tid + i * NTHREADS, gate = idx >> 9, n = (idx >> 4) & 31, kc = idx & 15;
;             *(LAS u32x4*)(WB + (gate * 32 + n) * XC_PITCH + kc * 16) = *(const u32x4*)(LruW + ((size_t)((dir * 2 + gate) * 8 + h) * 128 + q * 32 + n) * 128 + kc * 8); }
;         const float br = -LOG2E * P.lru_ba[(dir * 8 + h) * 128 + chl], bi = -LOG2E * P.lru_bx[(dir * 8 + h) * 128 + chl];
;         const float lam = P.lru_lambda[dir * 1024 + ch];
;         const float cl = -8.0f * LOG2E * log1pf(__expf(-lam));
; __device__ __forceinline__ void lru_strip(LAS unsigned char* lds, const Params& P, int strip, bool dry) {
;     const int tid = opaque_tid();
;     const int b = strip >> 5, h = (strip >> 2) & 7, q = strip & 3;
;     LAS float* CWL = (LAS float*)(lds + 256 * XC_PITCH + 2048 + 64 * XC_PITCH);
;     for (int i = tid; i < 640; i += NTHREADS) { const int k = i >> 7, c = i & 127; CWL[i] = k < 4 ? P.conv_w[k * 1024 + h * 128 + c] : P.conv_b[h * 128 + c]; }
;     LDS_BARRIER();
.LBB0_278:
	s_ashr_i32 s25, s2, 3
	v_mov_b32_e32 v128, v167
	s_bfe_u32 s26, s25, 0x30002
	s_lshl_b32 s27, s26, 7
	v_and_b32_e32 v204, 0x7f, v128
	v_or_b32_e32 v204, s27, v204
	v_lshrrev_b32_e32 v205, 7, v128
	v_lshl_or_b32 v205, v205, 10, v204
	v_lshlrev_b32_e32 v205, 2, v205
	v_lshlrev_b32_e32 v204, 2, v204
	global_load_dword v205, v205, s[52:53]
	global_load_dword v204, v204, s[54:55]
	v_readlane_b32 s0, v255, 19
	s_nop 3
	v_lshl_add_u32 v206, v128, 2, s0
	v_mov_b32_e32 v12, v167
	s_lshl_b32 s0, s25, 5
	s_and_b32 s28, s0, 0x60
	v_and_b32_e32 v15, 31, v12
	v_or_b32_e32 v17, s28, v15
	v_add_u32_e32 v14, 0x200, v12
	v_or_b32_e32 v11, s27, v17
	v_ashrrev_i32_e32 v8, 9, v12
	v_ashrrev_i32_e32 v10, 9, v14
	v_lshlrev_b32_e32 v16, 2, v11
	v_and_b32_e32 v13, 15, v12
	v_lshl_or_b32 v2, v8, 3, s26
	v_lshl_or_b32 v6, v10, 3, s26
	global_load_dword v18, v16, s[64:65]
	v_bfe_u32 v9, v12, 4, 5
	v_lshlrev_b32_e32 v64, 4, v13
	v_ashrrev_i32_e32 v3, 31, v2
	v_ashrrev_i32_e32 v7, 31, v6
	v_or_b32_e32 v4, s28, v9
	v_lshl_add_u64 v[0:1], s[38:39], 0, v[64:65]
	v_lshlrev_b64 v[2:3], 15, v[2:3]
	v_lshlrev_b64 v[6:7], 15, v[6:7]
	v_lshlrev_b32_e32 v4, 8, v4
	v_mov_b32_e32 v5, v65
	v_lshl_add_u64 v[2:3], v[0:1], 0, v[2:3]
	v_lshl_add_u64 v[0:1], v[0:1], 0, v[6:7]
	v_lshl_add_u64 v[2:3], v[2:3], 0, v[4:5]
	v_lshl_add_u64 v[4:5], v[0:1], 0, v[4:5]
	global_load_dwordx4 v[0:3], v[2:3], off
	s_nop 0
	global_load_dwordx4 v[4:7], v[4:5], off
	v_lshlrev_b32_e32 v11, 2, v12
	v_lshl_or_b32 v21, v8, 5, v9
	v_add_u32_e32 v8, s88, v64
	v_lshl_or_b32 v9, v10, 5, v9
	v_and_b32_e32 v22, 16, v11
	v_mad_u64_u32 v[10:11], s[4:5], v21, s89, v[8:9]
	v_mad_u64_u32 v[8:9], s[4:5], v9, s89, v[8:9]
	global_load_dword v9, v16, s[58:59]
	global_load_dword v11, v16, s[62:63]
	s_lshl_b32 s0, s2, 5
	s_and_b32 s0, s0, 0xe0
	s_or_b32 s1, s0, s25
	s_ashr_i32 s78, s1, 5
	s_ashr_i32 s79, s78, 31
	s_lshl_b32 s20, s26, 22
	s_lshl_b64 s[18:19], s[78:79], 19
	s_lshl_b64 s[44:45], s[78:79], 23
	v_readlane_b32 s1, v255, 18
	s_add_u32 s1, s1, s44
	s_addc_u32 s4, s33, s45
	s_lshl_b32 s5, s27, 2
	s_add_u32 s1, s1, s5
	s_addc_u32 s4, s4, 0
	s_add_u32 s5, s68, s18
	s_addc_u32 s6, s69, s19
	s_lshl_b32 s7, s27, 1
	s_add_u32 s48, s5, s7
	s_addc_u32 s49, s6, 0
	s_add_u32 s50, s48, 0x1000
	s_addc_u32 s51, s49, 0
	s_add_u32 s56, s48, 0x1800
	s_addc_u32 s57, s49, 0
	s_add_u32 s60, s48, 0x2000
	s_addc_u32 s61, s49, 0
	s_add_u32 s66, s48, 0x2800
	s_addc_u32 s67, s49, 0
	s_add_u32 s70, s48, 0x3000
	s_addc_u32 s71, s49, 0
	v_ashrrev_i32_e32 v36, 4, v12
	v_lshlrev_b32_e32 v37, 3, v13
	s_add_u32 s72, s48, 0x3800
	s_addc_u32 s73, s49, 0
	s_add_u32 s74, s48, 0x4000
	s_addc_u32 s75, s49, 0
	s_add_u32 s76, s48, 0x4800
	s_addc_u32 s77, s49, 0
	v_readfirstlane_b32 s0, v12
	s_ashr_i32 s6, s0, 6
	s_lshl_b32 s5, s28, 2
	s_add_u32 s8, s1, s5
	v_bfe_u32 v19, v12, 5, 1
	v_lshrrev_b32_e32 v20, 1, v12
	v_and_b32_e32 v33, 3, v12
	s_addc_u32 s9, s4, 0
	v_lshl_or_b32 v110, v36, 13, v37
	v_mov_b32_e32 v111, v65
	v_lshlrev_b64 v[110:111], 1, v[110:111]
	v_lshl_add_u64 v[108:109], s[48:49], 0, v[110:111]
	global_load_dwordx4 v[68:71], v[108:109], off offset:-2048
	global_load_dwordx4 v[72:75], v[108:109], off
	global_load_dwordx4 v[76:79], v[108:109], off offset:2048
	v_lshl_add_u64 v[108:109], s[50:51], 0, v[110:111]
	global_load_dwordx4 v[80:83], v[108:109], off
	v_lshl_add_u64 v[108:109], s[56:57], 0, v[110:111]
	global_load_dwordx4 v[84:87], v[108:109], off
	v_lshl_add_u64 v[108:109], s[60:61], 0, v[110:111]
	global_load_dwordx4 v[88:91], v[108:109], off
	v_lshl_add_u64 v[108:109], s[66:67], 0, v[110:111]
	global_load_dwordx4 v[92:95], v[108:109], off
	v_lshl_add_u64 v[108:109], s[70:71], 0, v[110:111]
	global_load_dwordx4 v[96:99], v[108:109], off
	v_lshl_add_u64 v[108:109], s[72:73], 0, v[110:111]
	global_load_dwordx4 v[100:103], v[108:109], off
	v_lshl_add_u64 v[108:109], s[74:75], 0, v[110:111]
	global_load_dwordx4 v[104:107], v[108:109], off
	v_lshl_add_u64 v[108:109], s[76:77], 0, v[110:111]
	global_load_dwordx4 v[108:111], v[108:109], off
	s_waitcnt vmcnt(14)
	ds_write_b128 v10, v[0:3]
	s_waitcnt vmcnt(13)
	ds_write_b128 v8, v[4:7]
	ds_write_b32 v206, v205
	v_cmp_gt_u32_e32 vcc, 0x80, v128
	s_and_saveexec_b64 s[14:15], vcc
	ds_write_b32 v206, v204 offset:2048
	s_or_b64 exec, exec, s[14:15]
	v_mul_f32_e32 v16, 0xbfb8aa3b, v18
	v_exp_f32_e32 v16, v16
	s_lshl_b32 s1, s6, 5
	s_and_b32 s0, s0, 0x3fffffc0
	v_add_u32_e32 v39, 0, v64
	v_add_f32_e32 v2, 1.0, v16
	v_add_f32_e32 v3, -1.0, v2
	v_frexp_mant_f32_e32 v4, v2
	v_cvt_f64_f32_e32 v[0:1], v2
	v_sub_f32_e32 v5, v3, v2
	v_frexp_exp_i32_f64_e32 v0, v[0:1]
	v_cmp_gt_f32_e32 vcc, s80, v4
	v_sub_f32_e32 v3, v16, v3
	v_add_f32_e32 v1, 1.0, v5
	v_subbrev_co_u32_e32 v0, vcc, 0, v0, vcc
	v_add_f32_e32 v1, v3, v1
	v_sub_u32_e32 v3, 0, v0
	v_ldexp_f32 v2, v2, v3
	v_ldexp_f32 v1, v1, v3
	v_add_f32_e32 v3, -1.0, v2
	v_add_f32_e32 v4, 1.0, v2
	v_add_f32_e32 v5, 1.0, v3
	v_add_f32_e32 v6, -1.0, v4
	v_sub_f32_e32 v5, v2, v5
	v_sub_f32_e32 v2, v2, v6
	v_add_f32_e32 v5, v1, v5
	v_add_f32_e32 v1, v1, v2
	v_add_f32_e32 v6, v4, v1
	v_rcp_f32_e32 v7, v6
	v_add_f32_e32 v2, v3, v5
	v_sub_f32_e32 v4, v6, v4
	v_sub_f32_e32 v3, v2, v3
	v_sub_f32_e32 v1, v1, v4
	v_mul_f32_e32 v4, v2, v7
	v_sub_f32_e32 v3, v5, v3
	v_mul_f32_e32 v5, v6, v4
	v_fma_f32 v8, v4, v6, -v5
	v_fmac_f32_e32 v8, v4, v1
	v_add_f32_e32 v10, v5, v8
	v_sub_f32_e32 v18, v2, v10
	v_sub_f32_e32 v2, v2, v18
	v_sub_f32_e32 v5, v10, v5
	v_sub_f32_e32 v2, v2, v10
	v_sub_f32_e32 v5, v5, v8
	v_add_f32_e32 v2, v3, v2
	v_add_f32_e32 v2, v5, v2
	v_add_f32_e32 v3, v18, v2
	v_mul_f32_e32 v5, v7, v3
	v_mul_f32_e32 v10, v6, v5
	v_fma_f32 v6, v5, v6, -v10
; #define LDS_BARRIER() do { asm volatile("s_waitcnt lgkmcnt(0)" ::: "memory"); __builtin_amdgcn_s_barrier(); asm volatile("" ::: "memory"); } while (0)
; template <int dir>
; __device__ __forceinline__ void lru_pass(LAS unsigned char* lds, const Params& P, int b, int h, int q, bool dry) {
;     ...
;         const float br = -LOG2E * P.lru_ba[(dir * 8 + h) * 128 + chl], bi = -LOG2E * P.lru_bx[(dir * 8 + h) * 128 + chl];
;         const float lam = P.lru_lambda[dir * 1024 + ch];
;         const float cl = -8.0f * LOG2E * log1pf(__expf(-lam));
;         float carry = 0.f;
;         LruTile cur = lru_tile(Z, ZC, b, h, dir, 0);
;         u32x4 rows[11];
;         constexpr int NIN = dir == 0 ? 2 : 4;
;         u32x4 inr[NIN];
;         lru_load_rows(rows, cur, tr, cgp);
; #pragma unroll
;         for (int i = 0; i < NIN; ++i) inr[i] = (u32x4){0u, 0u, 0u, 0u};
;         int t0_prev = 0;
; __device__ __forceinline__ void lru_strip(LAS unsigned char* lds, const Params& P, int strip, bool dry) {
;     ...
;     for (int i = tid; i < 640; i += NTHREADS) { const int k = i >> 7, c = i & 127; CWL[i] = k < 4 ? P.conv_w[k * 1024 + h * 128 + c] : P.conv_b[h * 128 + c]; }
;     LDS_BARRIER();
	v_fmac_f32_e32 v6, v5, v1
	v_add_f32_e32 v1, v10, v6
	v_sub_f32_e32 v8, v18, v3
	v_sub_f32_e32 v18, v3, v1
	v_sub_f32_e32 v3, v3, v18
	v_add_f32_e32 v2, v2, v8
	v_sub_f32_e32 v10, v1, v10
	v_sub_f32_e32 v1, v3, v1
	v_sub_f32_e32 v6, v10, v6
	v_add_f32_e32 v1, v2, v1
	v_cvt_f32_i32_e32 v0, v0
	v_add_f32_e32 v8, v4, v5
	v_add_f32_e32 v1, v6, v1
	v_add_f32_e32 v1, v18, v1
	v_sub_f32_e32 v2, v8, v4
	v_mul_f32_e32 v1, v7, v1
	v_sub_f32_e32 v2, v5, v2
	v_add_f32_e32 v1, v2, v1
	v_mul_f32_e32 v5, 0x3f317218, v0
	v_add_f32_e32 v2, v8, v1
	v_fma_f32 v6, v0, s81, -v5
	v_fmac_f32_e32 v6, 0xb102e308, v0
	v_sub_f32_e32 v0, v2, v8
	v_mul_f32_e32 v3, v2, v2
	v_sub_f32_e32 v0, v1, v0
	v_add_f32_e32 v1, v5, v6
	v_fmamk_f32 v4, v3, 0x3e9b6dac, v200
	v_sub_f32_e32 v5, v1, v5
	v_fmaak_f32 v4, v3, v4, 0x3f2aaada
	v_sub_f32_e32 v5, v6, v5
	v_ldexp_f32 v6, v2, 1
	v_mul_f32_e32 v2, v2, v3
	v_mul_f32_e32 v2, v2, v4
	v_add_f32_e32 v3, v6, v2
	v_sub_f32_e32 v4, v3, v6
	v_ldexp_f32 v0, v0, 1
	v_sub_f32_e32 v2, v2, v4
	v_add_f32_e32 v0, v0, v2
	v_add_f32_e32 v2, v3, v0
	v_sub_f32_e32 v3, v2, v3
	v_sub_f32_e32 v0, v0, v3
	v_add_f32_e32 v3, v1, v2
	v_sub_f32_e32 v4, v3, v1
	v_sub_f32_e32 v6, v3, v4
	v_sub_f32_e32 v1, v1, v6
	v_sub_f32_e32 v2, v2, v4
	v_add_f32_e32 v1, v2, v1
	v_add_f32_e32 v2, v5, v0
	v_sub_f32_e32 v4, v2, v5
	v_add_f32_e32 v1, v2, v1
	v_sub_f32_e32 v6, v2, v4
	v_add_f32_e32 v2, v3, v1
	v_sub_f32_e32 v5, v5, v6
	v_sub_f32_e32 v0, v0, v4
	v_sub_f32_e32 v3, v2, v3
	v_add_f32_e32 v0, v0, v5
	v_sub_f32_e32 v1, v1, v3
	v_add_f32_e32 v0, v0, v1
	v_add_f32_e32 v0, v2, v0
	v_cmp_neq_f32_e32 vcc, s91, v16
	v_mov_b32_e32 v1, v65
	v_lshlrev_b32_e32 v41, 4, v19
	v_cndmask_b32_e32 v0, v201, v0, vcc
	v_cmp_ngt_f32_e32 vcc, -1.0, v16
	s_cmp_eq_u32 s6, 7
	v_or_b32_e32 v35, s1, v41
	v_cndmask_b32_e32 v0, v202, v0, vcc
	v_cmp_neq_f32_e32 vcc, -1.0, v16
	v_ashrrev_i32_e32 v32, 2, v12
	v_ashrrev_i32_e32 v34, 2, v14
	v_cndmask_b32_e32 v0, v203, v0, vcc
	v_cmp_lt_f32_e64 vcc, |v16|, s92
	v_lshlrev_b32_e32 v53, 4, v33
	v_mul_lo_u32 v48, v32, s87
	v_cndmask_b32_e32 v6, v0, v16, vcc
	v_lshlrev_b32_e32 v1, 2, v15
	v_lshlrev_b32_e32 v2, 4, v12
	v_add_u32_e32 v140, s94, v1
	v_and_b32_e32 v3, 48, v2
	v_and_b32_e32 v64, 0x70, v2
	v_and_or_b32 v2, v20, 12, v33
	v_or3_b32 v2, v2, v22, s1
	v_lshl_add_u32 v147, s0, 2, v140
	s_cselect_b64 s[0:1], -1, 0
	s_cmp_eq_u32 s6, 6
	s_cselect_b64 s[16:17], -1, 0
	s_cmp_eq_u32 s6, 5
	s_cselect_b64 s[4:5], -1, 0
	s_cmp_eq_u32 s6, 4
	v_lshl_add_u64 v[130:131], s[8:9], 0, v[64:65]
	s_cselect_b64 s[8:9], -1, 0
	s_cmp_eq_u32 s6, 3
	s_cselect_b64 s[10:11], -1, 0
	s_cmp_eq_u32 s6, 2
	s_cselect_b64 s[12:13], -1, 0
	s_cmp_eq_u32 s6, 1
	s_cselect_b64 s[14:15], -1, 0
	s_add_u32 s46, s20, s18
	s_addc_u32 s47, 0, s19
	s_lshl_b32 s6, s2, 3
	v_ashrrev_i32_e32 v33, 31, v32
	v_mul_lo_u32 v50, v35, s89
	v_mul_lo_u32 v51, v35, s87
	v_mul_lo_u32 v52, v35, s30
	v_ashrrev_i32_e32 v35, 31, v34
	s_bfe_u32 s29, s2, 0x20003
	s_and_b32 s6, s6, 0xc0
	v_lshlrev_b64 v[32:33], 8, v[32:33]
	v_mul_lo_u32 v2, v2, s89
	v_add_u32_e32 v46, s96, v1
	v_mul_lo_u32 v49, v34, s87
	v_add_u32_e32 v1, 0x400, v12
	v_lshlrev_b64 v[34:35], 8, v[34:35]
	v_lshl_add_u64 v[32:33], s[46:47], 0, v[32:33]
	s_add_u32 s18, s82, s46
	v_lshlrev_b32_e32 v38, 5, v13
	v_add_u32_e32 v129, s96, v64
	v_add_u32_e32 v42, 0, v2
	v_mov_b32_e32 v2, s88
	v_ashrrev_i32_e32 v143, 3, v1
	v_add_u32_e32 v1, 0x600, v12
	v_lshl_add_u64 v[34:35], s[46:47], 0, v[34:35]
	v_or3_b32 v32, v32, s6, v53
	v_lshl_or_b32 v64, v36, 10, v37
	s_addc_u32 s19, s83, s47
	v_mov_b32_e32 v66, v65
	v_mov_b32_e32 v67, v65
	s_waitcnt vmcnt(12)
	v_mul_f32_e32 v0, 0xbfb8aa3b, v9
	s_waitcnt vmcnt(11)
	v_mul_f32_e32 v16, 0xbfb8aa3b, v11
	v_add_u32_e32 v40, s95, v3
	v_mad_u32_u24 v43, v15, s89, v2
	v_lshl_add_u32 v44, v17, 1, 0
	v_lshl_add_u32 v45, v15, 1, s95
	v_mul_lo_u32 v47, v36, s93
	v_ashrrev_i32_e32 v148, 3, v12
	v_ashrrev_i32_e32 v145, 3, v14
	v_ashrrev_i32_e32 v141, 3, v1
	v_or3_b32 v34, v34, s6, v53
	v_lshl_add_u64 v[134:135], s[40:41], 0, v[32:33]
	v_lshl_add_u64 v[136:137], v[64:65], 1, s[18:19]
	v_mov_b32_e32 v64, v65
	v_add_u32_e32 v32, 0, v38
	v_mov_b64_e32 v[114:115], v[66:67]
	v_mov_b64_e32 v[118:119], v[66:67]
	s_mov_b32 s90, 0
	v_mul_f32_e32 v138, 0xc138aa3b, v6
	v_lshl_add_u32 v139, v36, 3, -1
	v_cmp_eq_u32_e32 vcc, 0, v19
	v_mul_lo_u32 v149, v148, s30
	v_mul_lo_u32 v146, v145, s30
	v_mul_lo_u32 v144, v143, s30
	v_mul_lo_u32 v142, v141, s30
	v_mov_b32_e32 v1, v0
	v_mov_b32_e32 v2, v0
	v_mov_b32_e32 v3, v0
	v_mov_b32_e32 v4, v0
	v_mov_b32_e32 v5, v0
	v_mov_b32_e32 v6, v0
	v_mov_b32_e32 v7, v0
	v_mov_b32_e32 v8, v0
	v_mov_b32_e32 v9, v0
	v_mov_b32_e32 v10, v0
	v_mov_b32_e32 v11, v0
	v_mov_b32_e32 v12, v0
	v_mov_b32_e32 v13, v0
	v_mov_b32_e32 v14, v0
	v_mov_b32_e32 v15, v0
	v_mov_b32_e32 v17, v16
	v_mov_b32_e32 v18, v16
	v_mov_b32_e32 v19, v16
	v_mov_b32_e32 v20, v16
	v_mov_b32_e32 v21, v16
	v_mov_b32_e32 v22, v16
	v_mov_b32_e32 v23, v16
	v_mov_b32_e32 v24, v16
	v_mov_b32_e32 v25, v16
	v_mov_b32_e32 v26, v16
	v_mov_b32_e32 v27, v16
	v_mov_b32_e32 v28, v16
	v_mov_b32_e32 v29, v16
	v_mov_b32_e32 v30, v16
	v_mov_b32_e32 v31, v16
	v_lshl_add_u64 v[132:133], s[40:41], 0, v[34:35]
	s_movk_i32 s92, 0x100
	v_mov_b32_e32 v165, 0
	s_mov_b64 s[80:81], 0
	v_add_u32_e32 v150, 0x15c00, v32
	v_add_u32_e32 v151, v39, v47
	v_add_u32_e32 v158, v40, v48
	v_add_u32_e32 v159, v40, v49
	v_add_u32_e32 v160, v42, v41
	v_add_u32_e32 v161, v43, v41
	v_add_u32_e32 v162, v44, v50
	v_add_u32_e32 v163, v45, v51
	v_add_u32_e32 v164, v46, v52
	v_mov_b64_e32 v[112:113], v[64:65]
	v_mov_b64_e32 v[116:117], v[64:65]
	s_mov_b32 s91, 0
	s_mov_b32 s93, 0
	s_mov_b32 s97, 0
	s_waitcnt lgkmcnt(0)
	s_barrier
